# pvprio_s + nt (non-temporal) hint on the 48 dwordx4 input loads of the prologue phase (x and f32 weights are read exactly once)
# speedup vs baseline: 1.0058x; 1.0051x over previous
; #define LAS __attribute__((address_space(3)))
; #define GAS __attribute__((address_space(1)))
; __device__ __forceinline__ unsigned cvtpk(float lo, float hi) { f32x2 v = {lo, hi}; bf16x2_t b = __builtin_convertvector(v, bf16x2_t); return __builtin_bit_cast(unsigned, b); }
; #define LDS_WAIT() asm volatile("s_waitcnt lgkmcnt(0)" ::: "memory")
; __device__ __forceinline__ void transpose_item(const float* W, const float* gain, int K, int N, bf16_t* WT, LAS float* scr, int item, int lane) {
;     const int nblk = N / 32, kb = item / nblk, nb = item % nblk, k0 = 64 * kb, n0 = 32 * nb;
;     f32x4 wv[8]; float gk[8];
; #pragma unroll
;     for (int i = 0; i < 8; ++i) { const int kk = (lane >> 3) + 8 * i; wv[i] = *(const GAS f32x4*)((const GAS float*)W + (size_t)(k0 + kk) * N + n0 + 4 * (lane & 7)); gk[i] = gain ? gain[k0 + kk] : 1.0f; }
; #pragma unroll
;     for (int i = 0; i < 8; ++i) { const int kk = (lane >> 3) + 8 * i; LAS float* d = scr + kk * 33 + 4 * (lane & 7);
;         d[0] = wv[i][0] * gk[i]; d[1] = wv[i][1] * gk[i]; d[2] = wv[i][2] * gk[i]; d[3] = wv[i][3] * gk[i]; }
;     LDS_WAIT(); asm volatile("" ::: "memory");
;     const int c = lane & 7;
; #pragma unroll
;     for (int j = 0; j < 4; ++j) { const int n = (lane >> 3) + 8 * j; const LAS float* s = scr + (8 * c) * 33 + n;
;         u32x4 o; o.x = cvtpk(s[0 * 33], s[1 * 33]); o.y = cvtpk(s[2 * 33], s[3 * 33]); o.z = cvtpk(s[4 * 33], s[5 * 33]); o.w = cvtpk(s[6 * 33], s[7 * 33]);
;         *(u32x4*)(WT + (size_t)(n0 + n) * K + k0 + 8 * c) = o; }
;     LDS_WAIT(); asm volatile("" ::: "memory");
; }
; __global__ void __launch_bounds__(NWAVES * 64, 2) fwd_kernel(Args args) {
;     ...
;             transpose_item(w_down + (size_t)l * DFF * D, nullptr, DFF, D, (bf16_t*)(wl + W_IN_B + W_OUT_B + W_UP_B), scr, r, lane);
.LBB0_12:
	s_mul_hi_i32 s0, s38, 0xb21642c9
	s_add_i32 s0, s0, s38
	s_lshr_b32 s1, s0, 31
	s_ashr_i32 s0, s0, 12
	s_add_i32 s24, s0, s1
	s_mul_i32 s0, s24, 0xffffe900
	s_add_i32 s40, s38, s0
	s_ashr_i32 s25, s24, 31
	s_mul_i32 s1, s24, 0x1700000
	v_readlane_b32 s26, v252, 37
	s_mul_hi_i32 s0, s24, 0x1700000
	s_add_u32 s39, s26, s1
	v_readlane_b32 s1, v252, 38
	s_addc_u32 s56, s1, s0
	s_cmpk_gt_i32 s40, 0x47f
	s_mov_b64 s[0:1], -1
	s_cbranch_scc0 .LBB0_54
	s_cmpk_gt_u32 s40, 0x67f
	s_cbranch_scc0 .LBB0_35
	s_cmpk_gt_u32 s40, 0x117f
	s_cbranch_scc0 .LBB0_16
	v_readlane_b32 s80, v252, 5
	s_mul_i32 s1, s24, 0xb00000
	v_readlane_b32 s88, v252, 13
	s_mul_hi_i32 s0, s24, 0xb00000
	v_readlane_b32 s89, v252, 14
	s_add_u32 s1, s88, s1
	s_addc_u32 s26, s89, s0
	s_mul_i32 s0, s24, 0xffffd200
	s_add_i32 s0, s9, s0
	s_addk_i32 s0, 0xe600
	s_and_b32 s41, s3, 0x3e0
	s_and_b32 s27, s0, 0x1ffc0
	s_lshl_b32 s0, s41, 2
	s_add_u32 s0, s1, s0
	v_or_b32_e32 v2, s27, v33
	s_addc_u32 s1, s26, 0
	v_mov_b32_e32 v37, v35
	v_lshl_add_u64 v[0:1], s[0:1], 0, v[36:37]
	v_lshlrev_b32_e32 v34, 12, v2
	v_lshl_add_u64 v[28:29], v[0:1], 0, v[34:35]
	v_add_co_u32_e32 v4, vcc, s29, v28
	s_lshl_b32 s0, s27, 1
	s_nop 0
	v_addc_co_u32_e32 v5, vcc, 0, v29, vcc
	v_add_co_u32_e32 v8, vcc, s30, v28
	global_load_dwordx4 v[0:3], v[28:29], off nt
	s_nop 0
	global_load_dwordx4 v[4:7], v[4:5], off nt
	v_addc_co_u32_e32 v9, vcc, 0, v29, vcc
	v_add_co_u32_e32 v12, vcc, s31, v28
	s_add_u32 s0, s39, s0
	s_nop 0
	v_addc_co_u32_e32 v13, vcc, 0, v29, vcc
	v_add_co_u32_e32 v16, vcc, s33, v28
	global_load_dwordx4 v[8:11], v[8:9], off nt
	s_nop 0
	global_load_dwordx4 v[12:15], v[12:13], off nt
	v_addc_co_u32_e32 v17, vcc, 0, v29, vcc
	v_add_co_u32_e32 v20, vcc, s34, v28
	v_mov_b32_e32 v39, v35
	s_nop 0
	v_addc_co_u32_e32 v21, vcc, 0, v29, vcc
	global_load_dwordx4 v[16:19], v[16:17], off nt
	s_nop 0
	global_load_dwordx4 v[20:23], v[20:21], off nt
	v_add_co_u32_e32 v24, vcc, s35, v28
	v_or_b32_e32 v34, s41, v33
	s_nop 0
	v_addc_co_u32_e32 v25, vcc, 0, v29, vcc
	global_load_dwordx4 v[24:27], v[24:25], off nt
	v_add_co_u32_e32 v28, vcc, s36, v28
	s_addc_u32 s1, s56, 0
	s_nop 0
	v_addc_co_u32_e32 v29, vcc, 0, v29, vcc
	global_load_dwordx4 v[28:31], v[28:29], off nt
	v_mul_u32_u24_e32 v34, 0xb00, v34
	v_lshl_add_u64 v[42:43], s[0:1], 0, v[38:39]
	v_lshlrev_b32_e32 v34, 1, v34
	v_lshl_add_u64 v[42:43], v[42:43], 0, s[18:19]
	v_or_b32_e32 v37, s41, v41
	v_mul_u32_u24_e32 v37, 0xb00, v37
	v_readlane_b32 s81, v252, 6
	v_readlane_b32 s82, v252, 7
	v_readlane_b32 s83, v252, 8
	v_readlane_b32 s84, v252, 9
	v_readlane_b32 s85, v252, 10
	v_readlane_b32 s86, v252, 11
	v_readlane_b32 s87, v252, 12
	v_readlane_b32 s90, v252, 15
	v_readlane_b32 s91, v252, 16
	v_readlane_b32 s92, v252, 17
	v_readlane_b32 s93, v252, 18
	v_readlane_b32 s94, v252, 19
	v_readlane_b32 s95, v252, 20
	s_mov_b64 s[0:1], 0
	s_waitcnt vmcnt(7)
	ds_write2_b32 v51, v0, v1 offset1:1
	ds_write2_b32 v51, v2, v3 offset0:2 offset1:3
	s_waitcnt vmcnt(6)
	ds_write2_b32 v53, v4, v5 offset1:1
	ds_write2_b32 v57, v6, v7 offset1:1
	s_waitcnt vmcnt(5)
	ds_write2_b32 v58, v8, v9 offset1:1
	ds_write2_b32 v59, v10, v11 offset1:1
	s_waitcnt vmcnt(4)
	ds_write2_b32 v60, v12, v13 offset1:1
	ds_write2_b32 v61, v14, v15 offset1:1
	s_waitcnt vmcnt(3)
	ds_write2_b32 v62, v16, v17 offset1:1
	ds_write2_b32 v63, v18, v19 offset1:1
	s_waitcnt vmcnt(2)
	ds_write2_b32 v64, v20, v21 offset1:1
	ds_write2_b32 v65, v22, v23 offset1:1
	s_waitcnt vmcnt(1)
	ds_write2_b32 v66, v24, v25 offset1:1
	ds_write2_b32 v67, v26, v27 offset1:1
	s_waitcnt vmcnt(0)
	ds_write2_b32 v68, v28, v29 offset1:1
	ds_write2_b32 v69, v30, v31 offset1:1
	s_waitcnt lgkmcnt(0)
	ds_read2_b32 v[4:5], v49 offset0:33 offset1:41
	ds_read2_b32 v[6:7], v49 offset1:8
	ds_read2_b32 v[8:9], v49 offset0:66 offset1:74
	ds_read2_b32 v[10:11], v49 offset0:99 offset1:107
	ds_read2_b32 v[12:13], v49 offset0:132 offset1:140
	ds_read2_b32 v[14:15], v49 offset0:165 offset1:173
	ds_read2_b32 v[16:17], v49 offset0:198 offset1:206
	ds_read2_b32 v[18:19], v49 offset0:231 offset1:239
	v_lshl_add_u64 v[20:21], v[42:43], 0, v[34:35]
	s_waitcnt lgkmcnt(6)
	v_cvt_pk_bf16_f32 v0, v6, v4
	s_waitcnt lgkmcnt(4)
	v_cvt_pk_bf16_f32 v1, v8, v10
	s_waitcnt lgkmcnt(2)
	v_cvt_pk_bf16_f32 v2, v12, v14
	s_waitcnt lgkmcnt(0)
	v_cvt_pk_bf16_f32 v3, v16, v18
	global_store_dwordx4 v[20:21], v[0:3], off
	v_cvt_pk_bf16_f32 v4, v7, v5
	v_cvt_pk_bf16_f32 v5, v9, v11
	v_cvt_pk_bf16_f32 v6, v13, v15
	v_cvt_pk_bf16_f32 v7, v17, v19
	v_lshlrev_b32_e32 v34, 1, v37
	ds_read2_b32 v[8:9], v49 offset0:16 offset1:24
	ds_read2_b32 v[10:11], v49 offset0:49 offset1:57
	ds_read2_b32 v[12:13], v49 offset0:82 offset1:90
	ds_read2_b32 v[14:15], v49 offset0:115 offset1:123
	ds_read2_b32 v[16:17], v49 offset0:148 offset1:156
	ds_read2_b32 v[18:19], v49 offset0:181 offset1:189
	ds_read2_b32 v[20:21], v49 offset0:214 offset1:222
	ds_read2_b32 v[22:23], v49 offset0:247 offset1:255
	v_lshl_add_u64 v[0:1], v[42:43], 0, v[34:35]
	global_store_dwordx4 v[0:1], v[4:7], off
	s_waitcnt lgkmcnt(6)
	v_cvt_pk_bf16_f32 v0, v8, v10
	s_waitcnt lgkmcnt(4)
	v_cvt_pk_bf16_f32 v1, v12, v14
	v_or_b32_e32 v4, s41, v45
	v_mul_u32_u24_e32 v4, 0xb00, v4
	v_lshlrev_b32_e32 v34, 1, v4
	s_waitcnt lgkmcnt(2)
	v_cvt_pk_bf16_f32 v2, v16, v18
	s_waitcnt lgkmcnt(0)
	v_cvt_pk_bf16_f32 v3, v20, v22
	v_lshl_add_u64 v[4:5], v[42:43], 0, v[34:35]
	global_store_dwordx4 v[4:5], v[0:3], off
	v_or_b32_e32 v4, s41, v47
	v_mul_u32_u24_e32 v4, 0xb00, v4
	v_lshlrev_b32_e32 v34, 1, v4
	v_cvt_pk_bf16_f32 v0, v9, v11
	v_cvt_pk_bf16_f32 v1, v13, v15
	v_cvt_pk_bf16_f32 v2, v17, v19
	v_cvt_pk_bf16_f32 v3, v21, v23
	v_lshl_add_u64 v[4:5], v[42:43], 0, v[34:35]
	global_store_dwordx4 v[4:5], v[0:3], off
	s_waitcnt lgkmcnt(0)
; #define LAS __attribute__((address_space(3)))
; #define GAS __attribute__((address_space(1)))
; __device__ __forceinline__ void transpose_item(const float* W, const float* gain, int K, int N, bf16_t* WT, LAS float* scr, int item, int lane) {
;     const int nblk = N / 32, kb = item / nblk, nb = item % nblk, k0 = 64 * kb, n0 = 32 * nb;
;     f32x4 wv[8]; float gk[8];
; #pragma unroll
;     for (int i = 0; i < 8; ++i) { const int kk = (lane >> 3) + 8 * i; wv[i] = *(const GAS f32x4*)((const GAS float*)W + (size_t)(k0 + kk) * N + n0 + 4 * (lane & 7)); gk[i] = gain ? gain[k0 + kk] : 1.0f; }
; #pragma unroll
;     for (int i = 0; i < 8; ++i) { const int kk = (lane >> 3) + 8 * i; LAS float* d = scr + kk * 33 + 4 * (lane & 7);
;         d[0] = wv[i][0] * gk[i]; d[1] = wv[i][1] * gk[i]; d[2] = wv[i][2] * gk[i]; d[3] = wv[i][3] * gk[i]; }
; __global__ void __launch_bounds__(NWAVES * 64, 2) fwd_kernel(Args args) {
;     ...
;             if (r < I_UP) { transpose_item(w_up + (size_t)l * D * NUP, norm_ffn + l * D, D, NUP, (bf16_t*)(wl + W_IN_B + W_OUT_B), scr, r, lane); continue; } r -= I_UP;
.LBB0_16:
	s_andn2_b64 vcc, exec, s[0:1]
	s_cbranch_vccnz .LBB0_34
	v_readlane_b32 s80, v252, 5
	s_mul_i32 s1, s24, 0x1600000
	v_readlane_b32 s82, v252, 7
	s_mul_hi_i32 s0, s24, 0x1600000
	v_readlane_b32 s83, v252, 8
	s_add_u32 s43, s82, s1
	s_addc_u32 s44, s83, s0
	s_lshl_b32 s0, s24, 10
	s_ashr_i32 s1, s0, 31
	s_lshl_b64 s[0:1], s[0:1], 2
	v_readlane_b32 s81, v252, 6
	s_add_u32 s26, s80, s0
	s_addc_u32 s27, s81, s1
	s_add_i32 s0, s40, 0xf980
	s_and_b32 s1, s0, 0xffff
	s_mul_i32 s1, s1, 0xba2f
	s_lshr_b32 s1, s1, 23
	s_mul_i32 s41, s1, 0xb0
	s_sub_i32 s42, s0, s41
	s_lshl_b32 s0, s42, 7
	s_lshl_b32 s41, s1, 6
	s_and_b32 s0, s0, 0x3ff80
	s_add_u32 s0, s43, s0
	s_addc_u32 s1, s44, 0
	v_mov_b32_e32 v37, v35
	v_or_b32_e32 v30, s41, v33
	v_lshl_add_u64 v[28:29], s[0:1], 0, v[36:37]
	v_mad_u64_u32 v[0:1], s[0:1], v30, s37, v[28:29]
	global_load_dwordx4 v[0:3], v[0:1], off nt
	v_cndmask_b32_e64 v4, 0, 1, s[10:11]
	v_mov_b32_e32 v34, 1.0
	v_cmp_ne_u32_e64 s[0:1], 1, v4
	s_andn2_b64 vcc, exec, s[10:11]
	v_lshlrev_b32_e32 v37, 2, v30
	v_mov_b32_e32 v40, 1.0
	v_readlane_b32 s84, v252, 9
	v_readlane_b32 s85, v252, 10
	v_readlane_b32 s86, v252, 11
	v_readlane_b32 s87, v252, 12
	v_readlane_b32 s88, v252, 13
	v_readlane_b32 s89, v252, 14
	v_readlane_b32 s90, v252, 15
	v_readlane_b32 s91, v252, 16
	v_readlane_b32 s92, v252, 17
	v_readlane_b32 s93, v252, 18
	v_readlane_b32 s94, v252, 19
	v_readlane_b32 s95, v252, 20
	s_cbranch_vccnz .LBB0_19
	global_load_dword v40, v37, s[26:27]
.LBB0_19:
	v_or_b32_e32 v4, 8, v30
	v_mad_u64_u32 v[4:5], s[44:45], v4, s37, v[28:29]
	global_load_dwordx4 v[4:7], v[4:5], off nt
	s_and_b64 vcc, exec, s[0:1]
	s_cbranch_vccnz .LBB0_21
	global_load_dword v34, v37, s[26:27] offset:32
.LBB0_21:
	v_or_b32_e32 v8, 16, v30
	v_mad_u64_u32 v[8:9], s[44:45], v8, s37, v[28:29]
	global_load_dwordx4 v[8:11], v[8:9], off nt
	v_mov_b32_e32 v42, 1.0
	s_and_b64 vcc, exec, s[0:1]
	v_mov_b32_e32 v44, 1.0
	s_cbranch_vccnz .LBB0_23
	global_load_dword v44, v37, s[26:27] offset:64
.LBB0_23:
	v_or_b32_e32 v12, 24, v30
	v_mad_u64_u32 v[12:13], s[44:45], v12, s37, v[28:29]
	global_load_dwordx4 v[12:15], v[12:13], off nt
	s_and_b64 vcc, exec, s[0:1]
	s_cbranch_vccnz .LBB0_25
	global_load_dword v42, v37, s[26:27] offset:96
.LBB0_25:
	v_or_b32_e32 v16, 32, v30
	v_mad_u64_u32 v[16:17], s[44:45], v16, s37, v[28:29]
	global_load_dwordx4 v[16:19], v[16:17], off nt
	v_mov_b32_e32 v46, 1.0
	s_and_b64 vcc, exec, s[0:1]
	v_mov_b32_e32 v50, 1.0
	s_cbranch_vccnz .LBB0_27
	global_load_dword v50, v37, s[26:27] offset:128
.LBB0_27:
	v_or_b32_e32 v20, 40, v30
	v_mad_u64_u32 v[20:21], s[44:45], v20, s37, v[28:29]
	global_load_dwordx4 v[20:23], v[20:21], off nt
	s_and_b64 vcc, exec, s[0:1]
	s_cbranch_vccnz .LBB0_29
	global_load_dword v46, v37, s[26:27] offset:160
.LBB0_29:
	v_or_b32_e32 v24, 48, v30
	v_mad_u64_u32 v[24:25], s[44:45], v24, s37, v[28:29]
	global_load_dwordx4 v[24:27], v[24:25], off nt
	v_mov_b32_e32 v52, 1.0
	s_and_b64 vcc, exec, s[0:1]
	v_mov_b32_e32 v54, 1.0
	s_cbranch_vccnz .LBB0_31
	global_load_dword v54, v37, s[26:27] offset:192
.LBB0_31:
	v_or_b32_e32 v30, 56, v30
	v_mad_u64_u32 v[28:29], s[44:45], v30, s37, v[28:29]
	global_load_dwordx4 v[28:31], v[28:29], off nt
	s_and_b64 vcc, exec, s[0:1]
	s_cbranch_vccnz .LBB0_33
	global_load_dword v52, v37, s[26:27] offset:224

; #define LAS __attribute__((address_space(3)))
; #define GAS __attribute__((address_space(1)))
; __device__ __forceinline__ void transpose_item(const float* W, const float* gain, int K, int N, bf16_t* WT, LAS float* scr, int item, int lane) {
;     const int nblk = N / 32, kb = item / nblk, nb = item % nblk, k0 = 64 * kb, n0 = 32 * nb;
;     f32x4 wv[8]; float gk[8];
; #pragma unroll
;     for (int i = 0; i < 8; ++i) { const int kk = (lane >> 3) + 8 * i; wv[i] = *(const GAS f32x4*)((const GAS float*)W + (size_t)(k0 + kk) * N + n0 + 4 * (lane & 7)); gk[i] = gain ? gain[k0 + kk] : 1.0f; }
; #pragma unroll
;     for (int i = 0; i < 8; ++i) { const int kk = (lane >> 3) + 8 * i; LAS float* d = scr + kk * 33 + 4 * (lane & 7);
;         d[0] = wv[i][0] * gk[i]; d[1] = wv[i][1] * gk[i]; d[2] = wv[i][2] * gk[i]; d[3] = wv[i][3] * gk[i]; }
; __global__ void __launch_bounds__(NWAVES * 64, 2) fwd_kernel(Args args) {
;     ...
;             if (r < I_OUT) { transpose_item(w_out + (size_t)l * D * D, norm_grp + l * D, D, D, (bf16_t*)(wl + W_IN_B), scr, r, lane); continue; } r -= I_OUT;
.LBB0_35:
	s_andn2_b64 vcc, exec, s[0:1]
	s_cbranch_vccnz .LBB0_53
	v_readlane_b32 s80, v252, 21
	s_lshl_b64 s[0:1], s[24:25], 22
	v_readlane_b32 s94, v252, 35
	v_readlane_b32 s95, v252, 36
	s_add_u32 s42, s94, s0
	s_addc_u32 s43, s95, s1
	s_lshl_b32 s0, s24, 10
	s_ashr_i32 s1, s0, 31
	v_readlane_b32 s92, v252, 33
	s_lshl_b64 s[0:1], s[0:1], 2
	v_readlane_b32 s93, v252, 34
	s_add_u32 s26, s92, s0
	s_mul_i32 s0, s24, 0xffffd200
	s_addc_u32 s27, s93, s1
	s_add_i32 s0, s9, s0
	s_and_b32 s25, s3, 0x3e0
	s_and_b32 s41, s0, 0x1ffc0
	s_lshl_b32 s0, s25, 2
	s_add_u32 s0, s42, s0
	v_or_b32_e32 v30, s41, v33
	s_addc_u32 s1, s43, 0
	v_mov_b32_e32 v37, v35
	v_lshl_add_u64 v[28:29], s[0:1], 0, v[36:37]
	v_lshlrev_b32_e32 v34, 12, v30
	v_lshl_add_u64 v[0:1], v[28:29], 0, v[34:35]
	global_load_dwordx4 v[0:3], v[0:1], off nt
	v_cndmask_b32_e64 v4, 0, 1, s[12:13]
	v_mov_b32_e32 v40, 1.0
	v_cmp_ne_u32_e64 s[0:1], 1, v4
	s_andn2_b64 vcc, exec, s[12:13]
	v_lshlrev_b32_e32 v37, 2, v30
	v_mov_b32_e32 v42, 1.0
	v_readlane_b32 s81, v252, 22
	v_readlane_b32 s82, v252, 23
	v_readlane_b32 s83, v252, 24
	v_readlane_b32 s84, v252, 25
	v_readlane_b32 s85, v252, 26
	v_readlane_b32 s86, v252, 27
	v_readlane_b32 s87, v252, 28
	v_readlane_b32 s88, v252, 29
	v_readlane_b32 s89, v252, 30
	v_readlane_b32 s90, v252, 31
	v_readlane_b32 s91, v252, 32
	s_cbranch_vccnz .LBB0_38
	global_load_dword v42, v37, s[26:27]
.LBB0_38:
	v_lshl_or_b32 v34, v30, 12, v70
	v_lshl_add_u64 v[4:5], v[28:29], 0, v[34:35]
	global_load_dwordx4 v[4:7], v[4:5], off nt
	s_and_b64 vcc, exec, s[0:1]
	s_cbranch_vccnz .LBB0_40
	global_load_dword v40, v37, s[26:27] offset:32
.LBB0_40:
	v_lshl_or_b32 v34, v30, 12, v71
	v_lshl_add_u64 v[8:9], v[28:29], 0, v[34:35]
	global_load_dwordx4 v[8:11], v[8:9], off nt
	v_mov_b32_e32 v44, 1.0
	s_and_b64 vcc, exec, s[0:1]
	v_mov_b32_e32 v46, 1.0
	s_cbranch_vccnz .LBB0_42
	global_load_dword v46, v37, s[26:27] offset:64
.LBB0_42:
	v_lshl_or_b32 v34, v30, 12, v72
	v_lshl_add_u64 v[12:13], v[28:29], 0, v[34:35]
	global_load_dwordx4 v[12:15], v[12:13], off nt
	s_and_b64 vcc, exec, s[0:1]
	s_cbranch_vccnz .LBB0_44
	global_load_dword v44, v37, s[26:27] offset:96
.LBB0_44:
	v_lshl_or_b32 v34, v30, 12, v73
	v_lshl_add_u64 v[16:17], v[28:29], 0, v[34:35]
	global_load_dwordx4 v[16:19], v[16:17], off nt
	v_mov_b32_e32 v50, 1.0
	s_and_b64 vcc, exec, s[0:1]
	v_mov_b32_e32 v52, 1.0
	s_cbranch_vccnz .LBB0_46
	global_load_dword v52, v37, s[26:27] offset:128
.LBB0_46:
	v_lshl_or_b32 v34, v30, 12, v74
	v_lshl_add_u64 v[20:21], v[28:29], 0, v[34:35]
	global_load_dwordx4 v[20:23], v[20:21], off nt
	s_and_b64 vcc, exec, s[0:1]
	s_cbranch_vccnz .LBB0_48
	global_load_dword v50, v37, s[26:27] offset:160
.LBB0_48:
	v_lshl_or_b32 v34, v30, 12, v75
	v_lshl_add_u64 v[24:25], v[28:29], 0, v[34:35]
	global_load_dwordx4 v[24:27], v[24:25], off nt
	v_mov_b32_e32 v54, 1.0
	s_and_b64 vcc, exec, s[0:1]
	v_mov_b32_e32 v56, 1.0
	s_cbranch_vccnz .LBB0_50
	global_load_dword v56, v37, s[26:27] offset:192
.LBB0_50:
	v_lshl_or_b32 v34, v30, 12, v76
	v_lshl_add_u64 v[28:29], v[28:29], 0, v[34:35]
	global_load_dwordx4 v[28:31], v[28:29], off nt
	s_and_b64 vcc, exec, s[0:1]
	s_cbranch_vccnz .LBB0_52
	global_load_dword v54, v37, s[26:27] offset:224

; #define LAS __attribute__((address_space(3)))
; #define GAS __attribute__((address_space(1)))
; __device__ __forceinline__ void transpose_item(const float* W, const float* gain, int K, int N, bf16_t* WT, LAS float* scr, int item, int lane) {
;     const int nblk = N / 32, kb = item / nblk, nb = item % nblk, k0 = 64 * kb, n0 = 32 * nb;
;     f32x4 wv[8]; float gk[8];
; #pragma unroll
;     for (int i = 0; i < 8; ++i) { const int kk = (lane >> 3) + 8 * i; wv[i] = *(const GAS f32x4*)((const GAS float*)W + (size_t)(k0 + kk) * N + n0 + 4 * (lane & 7)); gk[i] = gain ? gain[k0 + kk] : 1.0f; }
; #pragma unroll
;     for (int i = 0; i < 8; ++i) { const int kk = (lane >> 3) + 8 * i; LAS float* d = scr + kk * 33 + 4 * (lane & 7);
;         d[0] = wv[i][0] * gk[i]; d[1] = wv[i][1] * gk[i]; d[2] = wv[i][2] * gk[i]; d[3] = wv[i][3] * gk[i]; }
; __global__ void __launch_bounds__(NWAVES * 64, 2) fwd_kernel(Args args) {
;     ...
;             if (r < I_IN) { transpose_item(w_in + (size_t)l * D * NIN, norm_mix + l * D, D, NIN, (bf16_t*)wl, scr, r, lane); continue; } r -= I_IN;
.LBB0_54:
	s_andn2_b64 vcc, exec, s[0:1]
	s_cbranch_vccnz .LBB0_11
	v_readlane_b32 s80, v252, 21
	s_mul_i32 s1, s24, 0x900000
	v_readlane_b32 s86, v252, 27
	s_mul_hi_i32 s0, s24, 0x900000
	v_readlane_b32 s87, v252, 28
	s_add_u32 s27, s86, s1
	s_addc_u32 s41, s87, s0
	s_lshl_b32 s0, s24, 10
	s_ashr_i32 s1, s0, 31
	v_readlane_b32 s84, v252, 25
	s_lshl_b64 s[0:1], s[0:1], 2
	v_readlane_b32 s85, v252, 26
	s_add_u32 s42, s84, s0
	s_mul_i32 s0, s40, 0xe39
	s_addc_u32 s43, s85, s1
	s_lshr_b32 s1, s0, 31
	s_ashr_i32 s0, s0, 18
	s_add_i32 s0, s0, s1
	s_mul_i32 s1, s0, 0x48
	s_sub_i32 s1, s40, s1
	s_sext_i32_i16 s1, s1
	s_lshl_b32 s24, s1, 5
	s_ashr_i32 s25, s24, 31
	s_lshl_b32 s26, s0, 6
	s_lshl_b64 s[0:1], s[24:25], 2
	s_add_u32 s0, s27, s0
	v_or_b32_e32 v28, s26, v33
	s_addc_u32 s1, s41, s1
	v_mov_b32_e32 v37, v35
	v_lshl_add_u64 v[30:31], s[0:1], 0, v[36:37]
	v_mul_hi_i32_i24_e32 v1, 0x2400, v28
	v_mul_i32_i24_e32 v0, 0x2400, v28
	v_lshl_add_u64 v[0:1], v[30:31], 0, v[0:1]
	global_load_dwordx4 v[0:3], v[0:1], off nt
	v_ashrrev_i32_e32 v29, 31, v28
	v_cndmask_b32_e64 v4, 0, 1, s[16:17]
	v_mov_b32_e32 v34, 1.0
	v_cmp_ne_u32_e64 s[0:1], 1, v4
	s_andn2_b64 vcc, exec, s[16:17]
	v_lshl_add_u64 v[42:43], v[28:29], 2, s[42:43]
	v_mov_b32_e32 v40, 1.0
	v_readlane_b32 s81, v252, 22
	v_readlane_b32 s82, v252, 23
	v_readlane_b32 s83, v252, 24
	v_readlane_b32 s88, v252, 29
	v_readlane_b32 s89, v252, 30
	v_readlane_b32 s90, v252, 31
	v_readlane_b32 s91, v252, 32
	v_readlane_b32 s92, v252, 33
	v_readlane_b32 s93, v252, 34
	v_readlane_b32 s94, v252, 35
	v_readlane_b32 s95, v252, 36
	s_cbranch_vccnz .LBB0_57
	global_load_dword v40, v[42:43], off
.LBB0_57:
	v_or_b32_e32 v4, 8, v28
	v_mul_hi_i32_i24_e32 v5, 0x2400, v4
	v_mul_i32_i24_e32 v4, 0x2400, v4
	v_lshl_add_u64 v[4:5], v[30:31], 0, v[4:5]
	global_load_dwordx4 v[4:7], v[4:5], off nt
	s_and_b64 vcc, exec, s[0:1]
	s_cbranch_vccnz .LBB0_59
	global_load_dword v34, v[42:43], off offset:32
.LBB0_59:
	v_or_b32_e32 v8, 16, v28
	v_mul_hi_i32_i24_e32 v9, 0x2400, v8
	v_mul_i32_i24_e32 v8, 0x2400, v8
	v_lshl_add_u64 v[8:9], v[30:31], 0, v[8:9]
	global_load_dwordx4 v[8:11], v[8:9], off nt
	v_mov_b32_e32 v44, 1.0
	s_and_b64 vcc, exec, s[0:1]
	v_mov_b32_e32 v46, 1.0
	s_cbranch_vccnz .LBB0_61
	global_load_dword v46, v[42:43], off offset:64
.LBB0_61:
	v_or_b32_e32 v12, 24, v28
	v_mul_hi_i32_i24_e32 v13, 0x2400, v12
	v_mul_i32_i24_e32 v12, 0x2400, v12
	v_lshl_add_u64 v[12:13], v[30:31], 0, v[12:13]
	global_load_dwordx4 v[12:15], v[12:13], off nt
	s_and_b64 vcc, exec, s[0:1]
	s_cbranch_vccnz .LBB0_63
	global_load_dword v44, v[42:43], off offset:96
.LBB0_63:
	v_or_b32_e32 v16, 32, v28
	v_mul_hi_i32_i24_e32 v17, 0x2400, v16
	v_mul_i32_i24_e32 v16, 0x2400, v16
	v_lshl_add_u64 v[16:17], v[30:31], 0, v[16:17]
	global_load_dwordx4 v[16:19], v[16:17], off nt
	v_mov_b32_e32 v50, 1.0
	s_and_b64 vcc, exec, s[0:1]
	v_mov_b32_e32 v52, 1.0
	s_cbranch_vccnz .LBB0_65
	global_load_dword v52, v[42:43], off offset:128
.LBB0_65:
	v_or_b32_e32 v20, 40, v28
	v_mul_hi_i32_i24_e32 v21, 0x2400, v20
	v_mul_i32_i24_e32 v20, 0x2400, v20
	v_lshl_add_u64 v[20:21], v[30:31], 0, v[20:21]
	global_load_dwordx4 v[20:23], v[20:21], off nt
	s_and_b64 vcc, exec, s[0:1]
	s_cbranch_vccnz .LBB0_67
	global_load_dword v50, v[42:43], off offset:160
.LBB0_67:
	v_or_b32_e32 v24, 48, v28
	v_mul_hi_i32_i24_e32 v25, 0x2400, v24
	v_mul_i32_i24_e32 v24, 0x2400, v24
	v_lshl_add_u64 v[24:25], v[30:31], 0, v[24:25]
	global_load_dwordx4 v[24:27], v[24:25], off nt
	v_mov_b32_e32 v54, 1.0
	s_and_b64 vcc, exec, s[0:1]
	v_mov_b32_e32 v56, 1.0
	s_cbranch_vccnz .LBB0_69
	global_load_dword v56, v[42:43], off offset:192
.LBB0_69:
	v_or_b32_e32 v28, 56, v28
	v_mul_hi_i32_i24_e32 v29, 0x2400, v28
	v_mul_i32_i24_e32 v28, 0x2400, v28
	v_lshl_add_u64 v[28:29], v[30:31], 0, v[28:29]
	global_load_dwordx4 v[28:31], v[28:29], off nt
	s_and_b64 vcc, exec, s[0:1]
	s_cbranch_vccnz .LBB0_10
	global_load_dword v54, v[42:43], off offset:224
	s_branch .LBB0_10

; #define GAS __attribute__((address_space(1)))
; __device__ __forceinline__ unsigned cvtpk(float lo, float hi) { f32x2 v = {lo, hi}; bf16x2_t b = __builtin_convertvector(v, bf16x2_t); return __builtin_bit_cast(unsigned, b); }
; __global__ void __launch_bounds__(NWAVES * 64, 2) fwd_kernel(Args args) {
;     ...
;         for (int m0 = 4 * gw; m0 < M; m0 += 4 * NGW) {
;             f32x4 v[4][4];
; #pragma unroll
;             for (int r = 0; r < 4; ++r) { const int m = m0 + r; const GAS float* xr = (m < SEQ) ? (const GAS float*)x_p + (size_t)m * D : (const GAS float*)x_s + (size_t)(m - SEQ) * D;
; #pragma unroll
;                 for (int j = 0; j < 4; ++j) v[r][j] = *(const GAS f32x4*)(xr + 4 * lane + 256 * j); }
; #pragma unroll
;             for (int r = 0; r < 4; ++r) { const int m = m0 + r; float s = 0.f;
; #pragma unroll
;                 for (int j = 0; j < 4; ++j) s += (v[r][j][0] * v[r][j][0] + v[r][j][1] * v[r][j][1]) + (v[r][j][2] * v[r][j][2] + v[r][j][3] * v[r][j][3]);
;                 s = wave_sum(s);
; #pragma unroll
;                 for (int j = 0; j < 4; ++j) { u32x2 w; w.x = cvtpk(v[r][j][0], v[r][j][1]); w.y = cvtpk(v[r][j][2], v[r][j][3]); *(GAS u32x2*)((GAS bf16_t*)XB + (size_t)(m + m / SEQ) * D + 4 * lane + 256 * j) = w; }
;                 if (lane < 16) ((GAS float*)SSX)[(size_t)m * 16 + lane] = s * (1.0f / 16.0f); }
.LBB0_74:
	s_add_i32 s0, s10, 0xffffc000
	s_cmpk_lt_i32 s10, 0x4000
	v_readlane_b32 s36, v252, 21
	s_cselect_b32 s1, s11, 0
	s_cselect_b32 s0, s10, s0
	v_readlane_b32 s37, v252, 22
	v_readlane_b32 s38, v252, 23
	v_readlane_b32 s39, v252, 24
	s_cselect_b32 s7, s37, s39
	s_cselect_b32 s9, s36, s38
	s_lshl_b64 s[0:1], s[0:1], 12
	s_add_u32 s0, s9, s0
	s_addc_u32 s1, s7, s1
	global_load_dwordx4 v[62:65], v49, s[0:1] nt
	global_load_dwordx4 v[66:69], v49, s[0:1] offset:1024 nt
	global_load_dwordx4 v[70:73], v49, s[0:1] offset:2048 nt
	global_load_dwordx4 v[74:77], v49, s[0:1] offset:3072 nt
	s_add_u32 s20, s10, 1
	s_addc_u32 s0, s11, 0
	s_add_i32 s7, s10, 0xffffc001
	s_cmpk_lt_i32 s20, 0x4000
	s_cselect_b32 s1, s0, 0
	s_cselect_b32 s0, s20, s7
	s_cselect_b32 s7, s37, s39
	s_cselect_b32 s9, s36, s38
	s_lshl_b64 s[0:1], s[0:1], 12
	s_add_u32 s0, s9, s0
	s_addc_u32 s1, s7, s1
	s_add_u32 s9, s10, 2
	global_load_dwordx4 v[44:47], v49, s[0:1] nt
	global_load_dwordx4 v[40:43], v49, s[0:1] offset:1024 nt
	global_load_dwordx4 v[36:39], v49, s[0:1] offset:2048 nt
	global_load_dwordx4 v[32:35], v49, s[0:1] offset:3072 nt
	s_addc_u32 s0, s11, 0
	s_add_i32 s7, s10, 0xffffc002
	s_cmpk_lt_i32 s9, 0x4000
	s_cselect_b32 s1, s0, 0
	s_cselect_b32 s0, s9, s7
	s_cselect_b32 s7, s37, s39
	s_cselect_b32 s21, s36, s38
	s_lshl_b64 s[0:1], s[0:1], 12
	s_add_u32 s0, s21, s0
	s_addc_u32 s1, s7, s1
	s_add_u32 s7, s10, 3
	global_load_dwordx4 v[28:31], v49, s[0:1] nt
	global_load_dwordx4 v[24:27], v49, s[0:1] offset:1024 nt
	global_load_dwordx4 v[20:23], v49, s[0:1] offset:2048 nt
	s_waitcnt lgkmcnt(0)
	global_load_dwordx4 v[16:19], v49, s[0:1] offset:3072 nt
	s_addc_u32 s0, s11, 0
	s_add_i32 s21, s10, 0xffffc003
	s_cmpk_lt_i32 s7, 0x4000
	s_cselect_b32 s1, s0, 0
	s_cselect_b32 s0, s7, s21
	s_cselect_b32 s21, s37, s39
	s_cselect_b32 s22, s36, s38
	s_lshl_b64 s[0:1], s[0:1], 12
	s_add_u32 s0, s22, s0
	s_addc_u32 s1, s21, s1
	global_load_dwordx4 v[4:7], v49, s[0:1] nt
	global_load_dwordx4 v[0:3], v49, s[0:1] offset:1024 nt
	global_load_dwordx4 v[12:15], v49, s[0:1] offset:2048 nt
	global_load_dwordx4 v[8:11], v49, s[0:1] offset:3072 nt
	s_ashr_i32 s0, s10, 31
	s_lshr_b32 s0, s0, 18
	s_add_i32 s0, s10, s0
	s_ashr_i32 s0, s0, 14
	s_ashr_i32 s1, s0, 31
	s_add_u32 s0, s10, s0
	s_addc_u32 s1, s11, s1
	s_lshl_b64 s[0:1], s[0:1], 11
	v_readlane_b32 s40, v252, 25
	v_readlane_b32 s41, v252, 26
	v_readlane_b32 s42, v252, 27
	v_readlane_b32 s43, v252, 28
	v_readlane_b32 s44, v252, 29
	v_readlane_b32 s45, v252, 30
	v_readlane_b32 s46, v252, 31
	v_readlane_b32 s47, v252, 32
	v_readlane_b32 s48, v252, 33
	v_readlane_b32 s49, v252, 34
	v_readlane_b32 s50, v252, 35
	v_readlane_b32 s51, v252, 36
	s_waitcnt vmcnt(15)
	v_mul_f32_e32 v61, v63, v63
	v_mul_f32_e32 v78, v65, v65
	s_waitcnt vmcnt(14)
	v_mul_f32_e32 v79, v67, v67
	v_mul_f32_e32 v80, v69, v69
	s_waitcnt vmcnt(13)
	v_mul_f32_e32 v81, v71, v71
	v_mul_f32_e32 v82, v73, v73
	v_fmac_f32_e32 v61, v62, v62
	v_fmac_f32_e32 v78, v64, v64
	v_fmac_f32_e32 v79, v66, v66
	v_fmac_f32_e32 v80, v68, v68
	s_waitcnt vmcnt(12)
	v_mul_f32_e32 v83, v75, v75
	v_mul_f32_e32 v84, v77, v77
	v_fmac_f32_e32 v81, v70, v70
	v_fmac_f32_e32 v82, v72, v72
	v_add_f32_e32 v61, v61, v78
	v_add_f32_e32 v78, v79, v80
	v_fmac_f32_e32 v83, v74, v74
	v_fmac_f32_e32 v84, v76, v76
	v_add_f32_e32 v79, v81, v82
	v_add_f32_e32 v61, v61, v78
	v_add_f32_e32 v80, v83, v84
	v_add_f32_e32 v61, v61, v79
	v_add_f32_e32 v61, v61, v80
	ds_bpermute_b32 v78, v54, v61
	v_cvt_pk_bf16_f32 v62, v62, v63
	v_cvt_pk_bf16_f32 v63, v64, v65
	v_cvt_pk_bf16_f32 v64, v66, v67
	v_cvt_pk_bf16_f32 v65, v68, v69
	s_waitcnt lgkmcnt(0)
	v_add_f32_e32 v61, v61, v78
	ds_bpermute_b32 v78, v56, v61
	v_cvt_pk_bf16_f32 v66, v70, v71
	s_waitcnt lgkmcnt(0)
	v_add_f32_e32 v61, v61, v78
	ds_bpermute_b32 v78, v57, v61
	s_waitcnt lgkmcnt(0)
	v_add_f32_e32 v61, v61, v78
	ds_bpermute_b32 v80, v58, v61
	v_lshl_add_u64 v[78:79], v[50:51], 0, s[0:1]
	global_store_dwordx2 v[78:79], v[62:63], off
	global_store_dwordx2 v[78:79], v[64:65], off offset:512
	v_cvt_pk_bf16_f32 v64, v74, v75
	v_cvt_pk_bf16_f32 v65, v76, v77
	s_waitcnt lgkmcnt(0)
	v_add_f32_e32 v61, v61, v80
	ds_bpermute_b32 v67, v59, v61
	global_store_dwordx2 v[78:79], v[64:65], off offset:1536
	s_waitcnt lgkmcnt(0)
	v_add_f32_e32 v61, v61, v67
	ds_bpermute_b32 v62, v60, v61
	v_cvt_pk_bf16_f32 v67, v72, v73
	global_store_dwordx2 v[78:79], v[66:67], off offset:1024
	s_and_saveexec_b64 s[0:1], vcc
	s_cbranch_execz .LBB0_76
	s_waitcnt lgkmcnt(0)
	v_add_f32_e32 v61, v61, v62
	v_mul_f32_e32 v61, 0x3d800000, v61
	global_store_dword v[52:53], v61, off
